# sample queue: workgroup with the last unit index leaves without a further fetch
# baseline (speedup 1.0000x reference)
.LBB0_1425:
	v_mov_b32_e32 v0, s80
	ds_read_b32 v0, v0
	s_waitcnt lgkmcnt(0)
	v_readfirstlane_b32 s6, v0
	s_cmpk_eq_i32 s6, 0xff
	s_cselect_b64 s[6:7], -1, 0
	s_barrier
